# diff-attention band tiles: wave-uniform skip of the relative-position bias lookups when every lane's LUT index clamps to the zero entry (far or above-diagonal wave-tiles)
# baseline (speedup 1.0000x reference)
; __device__ __forceinline__ void biasd(f32x16&p0,f32x16&p1,const __attribute__((address_space(3))) float*lut,int base){
;   #pragma unroll
;   for(int r=0;r<16;++r){ const int d0=base-((r&3)+8*(r>>2)); unsigned i0=(unsigned)d0; i0=i0>127u?127u:i0; unsigned i1=(unsigned)(d0-32); i1=i1>127u?127u:i1; p0[r]+=lut[i0]; p1[r]+=lut[i1];
;     if((r&3)==3){ asm volatile("":"+v"(p0),"+v"(p1)); __builtin_amdgcn_sched_barrier(0); } }
; }
.LBB0_490:
	v_add_u32_e32 v15, v238, v253
	v_cmp_gt_u32_e32 vcc, 0xba, v15
	s_cbranch_vccnz .Lbias_full_l0a
	s_add_i32 s6, s41, 1
	s_lshl_b32 s93, s80, 1
	s_lshl_b32 s6, s6, 14
	s_add_i32 s7, s93, s81
	s_mov_b32 s40, m0
	s_mov_b32 m0, s7
	s_nop 0
	buffer_load_dwordx4 v248, s[16:19], s6 offen lds
	s_mov_b32 m0, s40
	s_bitset1_b32 s6, 7
	s_add_i32 s7, s93, s55
	s_mov_b32 s40, m0
	s_mov_b32 m0, s7
	s_nop 0
	buffer_load_dwordx4 v248, s[16:19], s6 offen lds
	s_mov_b32 m0, s40
	s_add_i32 s40, s92, s41
	s_waitcnt lgkmcnt(0)
	s_branch .Lbias_end_l0a
.Lbias_full_l0a:
	v_add_u32_e32 v82, -1, v15
	v_min_u32_e32 v82, 0x7f, v82
	v_lshl_add_u32 v84, v82, 2, s89
	v_add_u32_e32 v82, -2, v15
	s_add_i32 s6, s41, 1
	s_lshl_b32 s93, s80, 1
	v_subrev_u32_e32 v81, 32, v15
	v_subrev_u32_e32 v83, 33, v15
	v_min_u32_e32 v82, 0x7f, v82
	v_subrev_u32_e32 v85, 34, v15
	v_subrev_u32_e32 v87, 35, v15
	s_lshl_b32 s6, s6, 14
	s_add_i32 s7, s93, s81
	s_mov_b32 s40, m0
	s_mov_b32 m0, s7
	s_nop 0
	buffer_load_dwordx4 v248, s[16:19], s6 offen lds
	s_mov_b32 m0, s40
	v_min_u32_e32 v80, 0x7f, v15
	v_min_u32_e32 v81, 0x7f, v81
	v_min_u32_e32 v83, 0x7f, v83
	v_min_u32_e32 v85, 0x7f, v85
	v_lshl_add_u32 v86, v82, 2, s89
	v_add_u32_e32 v82, -3, v15
	v_min_u32_e32 v87, 0x7f, v87
	s_bitset1_b32 s6, 7
	s_add_i32 s7, s93, s55
	s_mov_b32 s40, m0
	s_mov_b32 m0, s7
	s_nop 0
	buffer_load_dwordx4 v248, s[16:19], s6 offen lds
	s_mov_b32 m0, s40
	v_lshl_add_u32 v80, v80, 2, s89
	v_lshl_add_u32 v81, v81, 2, s89
	v_lshl_add_u32 v83, v83, 2, s89
	v_lshl_add_u32 v85, v85, 2, s89
	v_min_u32_e32 v82, 0x7f, v82
	v_lshl_add_u32 v87, v87, 2, s89
	v_lshl_add_u32 v88, v82, 2, s89
	ds_read_b32 v80, v80
	ds_read_b32 v82, v81
	ds_read_b32 v81, v84
	ds_read_b32 v83, v83
	ds_read_b32 v84, v86
	ds_read_b32 v86, v85
	ds_read_b32 v85, v88
	ds_read_b32 v87, v87
	s_add_i32 s40, s92, s41
	s_waitcnt lgkmcnt(5)
	v_pk_add_f32 v[112:113], v[112:113], v[80:81]
	s_waitcnt lgkmcnt(4)
	v_pk_add_f32 v[128:129], v[128:129], v[82:83]
	s_waitcnt lgkmcnt(1)
	v_pk_add_f32 v[114:115], v[114:115], v[84:85]
	s_waitcnt lgkmcnt(0)
	v_pk_add_f32 v[130:131], v[130:131], v[86:87]
	s_nop 0
	v_add_u32_e32 v82, -9, v15
	v_min_u32_e32 v82, 0x7f, v82
	v_lshl_add_u32 v84, v82, 2, s89
	v_add_u32_e32 v82, -10, v15
	v_add_u32_e32 v80, -8, v15
	v_subrev_u32_e32 v81, 40, v15
	v_subrev_u32_e32 v83, 41, v15
	v_min_u32_e32 v82, 0x7f, v82
	v_subrev_u32_e32 v85, 42, v15
	v_subrev_u32_e32 v87, 43, v15
	v_min_u32_e32 v80, 0x7f, v80
	v_min_u32_e32 v81, 0x7f, v81
	v_min_u32_e32 v83, 0x7f, v83
	v_min_u32_e32 v85, 0x7f, v85
	v_lshl_add_u32 v86, v82, 2, s89
	v_add_u32_e32 v82, -11, v15
	v_min_u32_e32 v87, 0x7f, v87
	v_lshl_add_u32 v80, v80, 2, s89
	v_lshl_add_u32 v81, v81, 2, s89
	v_lshl_add_u32 v83, v83, 2, s89
	v_lshl_add_u32 v85, v85, 2, s89
	v_min_u32_e32 v82, 0x7f, v82
	v_lshl_add_u32 v87, v87, 2, s89
	v_lshl_add_u32 v88, v82, 2, s89
	ds_read_b32 v80, v80
	ds_read_b32 v82, v81
	ds_read_b32 v81, v84
	ds_read_b32 v83, v83
	ds_read_b32 v84, v86
	ds_read_b32 v86, v85
	ds_read_b32 v85, v88
	ds_read_b32 v87, v87
	s_waitcnt lgkmcnt(5)
	v_pk_add_f32 v[116:117], v[80:81], v[116:117]
	s_waitcnt lgkmcnt(4)
	v_pk_add_f32 v[132:133], v[132:133], v[82:83]
	s_waitcnt lgkmcnt(1)
	v_pk_add_f32 v[118:119], v[118:119], v[84:85]
	s_waitcnt lgkmcnt(0)
	v_pk_add_f32 v[134:135], v[134:135], v[86:87]
	s_nop 0
	v_subrev_u32_e32 v82, 17, v15
	v_min_u32_e32 v82, 0x7f, v82
	v_lshl_add_u32 v84, v82, 2, s89
	v_subrev_u32_e32 v82, 18, v15
	v_add_u32_e32 v80, -16, v15
	v_subrev_u32_e32 v81, 48, v15
	v_subrev_u32_e32 v83, 49, v15
	v_min_u32_e32 v82, 0x7f, v82
	v_subrev_u32_e32 v85, 50, v15
	v_subrev_u32_e32 v87, 51, v15
	v_min_u32_e32 v80, 0x7f, v80
	v_min_u32_e32 v81, 0x7f, v81
	v_min_u32_e32 v83, 0x7f, v83
	v_min_u32_e32 v85, 0x7f, v85
	v_lshl_add_u32 v86, v82, 2, s89
	v_subrev_u32_e32 v82, 19, v15
	v_min_u32_e32 v87, 0x7f, v87
	v_lshl_add_u32 v80, v80, 2, s89
	v_lshl_add_u32 v81, v81, 2, s89
	v_lshl_add_u32 v83, v83, 2, s89
	v_lshl_add_u32 v85, v85, 2, s89
	v_min_u32_e32 v82, 0x7f, v82
	v_lshl_add_u32 v87, v87, 2, s89
	v_lshl_add_u32 v88, v82, 2, s89
	ds_read_b32 v80, v80
	ds_read_b32 v82, v81
	ds_read_b32 v81, v84
	ds_read_b32 v83, v83
	ds_read_b32 v84, v86
	ds_read_b32 v86, v85
	ds_read_b32 v85, v88
	ds_read_b32 v87, v87
	s_waitcnt lgkmcnt(5)
	v_pk_add_f32 v[120:121], v[80:81], v[120:121]
	s_waitcnt lgkmcnt(4)
	v_pk_add_f32 v[136:137], v[136:137], v[82:83]
	s_waitcnt lgkmcnt(1)
	v_pk_add_f32 v[122:123], v[122:123], v[84:85]
	s_waitcnt lgkmcnt(0)
	v_pk_add_f32 v[138:139], v[138:139], v[86:87]
	s_nop 0
	v_subrev_u32_e32 v82, 25, v15
	v_min_u32_e32 v82, 0x7f, v82
	v_lshl_add_u32 v84, v82, 2, s89
	v_subrev_u32_e32 v82, 26, v15
	v_min_u32_e32 v82, 0x7f, v82
	v_subrev_u32_e32 v80, 24, v15
	v_subrev_u32_e32 v81, 56, v15
	v_subrev_u32_e32 v83, 57, v15
	v_subrev_u32_e32 v85, 58, v15
	v_lshl_add_u32 v86, v82, 2, s89
	v_subrev_u32_e32 v82, 27, v15
	v_min_u32_e32 v80, 0x7f, v80
	v_min_u32_e32 v81, 0x7f, v81
	v_min_u32_e32 v83, 0x7f, v83
	v_min_u32_e32 v85, 0x7f, v85
	v_min_u32_e32 v82, 0x7f, v82
	v_subrev_u32_e32 v15, 59, v15
	v_lshl_add_u32 v80, v80, 2, s89
	v_lshl_add_u32 v81, v81, 2, s89
	v_lshl_add_u32 v83, v83, 2, s89
	v_lshl_add_u32 v85, v85, 2, s89
	v_min_u32_e32 v15, 0x7f, v15
	v_lshl_add_u32 v87, v82, 2, s89
	v_lshl_add_u32 v15, v15, 2, s89
	ds_read_b32 v80, v80
	ds_read_b32 v82, v81
	ds_read_b32 v81, v84
	ds_read_b32 v83, v83
	ds_read_b32 v84, v86
	ds_read_b32 v86, v85
	ds_read_b32 v85, v87
	ds_read_b32 v87, v15
	s_waitcnt lgkmcnt(5)
	v_pk_add_f32 v[124:125], v[80:81], v[124:125]
	s_waitcnt lgkmcnt(4)
	v_pk_add_f32 v[140:141], v[140:141], v[82:83]
	s_waitcnt lgkmcnt(1)
	v_pk_add_f32 v[126:127], v[126:127], v[84:85]
	s_waitcnt lgkmcnt(0)
	v_pk_add_f32 v[142:143], v[142:143], v[86:87]
	s_nop 0
; __device__ __forceinline__ void cmask(f32x16&p0,f32x16&p1,int jb,int qrel,int hi){
;   const float NEG=-INFINITY; int kb=64*jb+4*hi;
;   #pragma unroll
;   for(int r=0;r<16;++r){int kv=kb+(r&3)+8*(r>>2); if(kv>qrel)p0[r]=NEG; if(kv+32>qrel)p1[r]=NEG;}
; }
.Lbias_end_l0a:
	s_cmp_lt_i32 s40, 0
	s_cbranch_scc1 .LBB0_492
	v_add_u32_e32 v80, 0xffffffa5, v0
	v_add_u32_e32 v15, 0xffffff85, v0
	v_cmp_le_i32_e32 vcc, v80, v246
	s_nop 1
	v_cndmask_b32_e32 v128, v235, v128, vcc
	v_cmp_lt_i32_e32 vcc, v15, v246
	s_nop 1
	v_cndmask_b32_e32 v113, v235, v113, vcc
	v_cmp_le_i32_e32 vcc, v15, v246
	v_add_u32_e32 v15, 0xffffffa6, v0
	s_nop 0
	v_cndmask_b32_e32 v112, v235, v112, vcc
	v_cmp_le_i32_e32 vcc, v15, v246
	v_add_u32_e32 v15, 0xffffff87, v0
	s_nop 0
	v_cndmask_b32_e32 v129, v235, v129, vcc
	v_cmp_le_i32_e32 vcc, v15, v246
	v_add_u32_e32 v15, 0xffffffa7, v0
	s_nop 0
	v_cndmask_b32_e32 v114, v235, v114, vcc
	v_cmp_le_i32_e32 vcc, v15, v246
	v_add_u32_e32 v15, 0xffffff88, v0
	s_nop 0
	v_cndmask_b32_e32 v130, v235, v130, vcc
	v_cmp_le_i32_e32 vcc, v15, v246
	v_add_u32_e32 v15, 0xffffffa8, v0
	s_nop 0
	v_cndmask_b32_e32 v115, v235, v115, vcc
	v_cmp_le_i32_e32 vcc, v15, v246
	v_add_u32_e32 v15, 0xffffff8d, v0
	s_nop 0
	v_cndmask_b32_e32 v131, v235, v131, vcc
	v_cmp_le_i32_e32 vcc, v15, v246
	v_add_u32_e32 v15, 0xffffffad, v0
	s_nop 0
	v_cndmask_b32_e32 v116, v235, v116, vcc
	v_cmp_le_i32_e32 vcc, v15, v246
	v_add_u32_e32 v15, 0xffffff8e, v0
	s_nop 0
	v_cndmask_b32_e32 v132, v235, v132, vcc
	v_cmp_le_i32_e32 vcc, v15, v246
	v_add_u32_e32 v15, 0xffffffae, v0
	s_nop 0
	v_cndmask_b32_e32 v117, v235, v117, vcc
	v_cmp_le_i32_e32 vcc, v15, v246
	v_add_u32_e32 v15, 0xffffff8f, v0
	s_nop 0
	v_cndmask_b32_e32 v133, v235, v133, vcc
	v_cmp_le_i32_e32 vcc, v15, v246
	v_add_u32_e32 v15, 0xffffffaf, v0
	s_nop 0
	v_cndmask_b32_e32 v118, v235, v118, vcc
	v_cmp_le_i32_e32 vcc, v15, v246
	v_add_u32_e32 v15, 0xffffff90, v0
	s_nop 0
	v_cndmask_b32_e32 v134, v235, v134, vcc
	v_cmp_le_i32_e32 vcc, v15, v246
	v_add_u32_e32 v15, 0xffffffb0, v0
	s_nop 0
	v_cndmask_b32_e32 v119, v235, v119, vcc
	v_cmp_le_i32_e32 vcc, v15, v246
	v_add_u32_e32 v15, 0xffffff95, v0
	s_nop 0
	v_cndmask_b32_e32 v135, v235, v135, vcc
	v_cmp_le_i32_e32 vcc, v15, v246
	v_add_u32_e32 v15, 0xffffffb5, v0
	s_nop 0
	v_cndmask_b32_e32 v120, v235, v120, vcc
	v_cmp_le_i32_e32 vcc, v15, v246
	v_add_u32_e32 v15, 0xffffff96, v0
	s_nop 0
	v_cndmask_b32_e32 v136, v235, v136, vcc
	v_cmp_le_i32_e32 vcc, v15, v246
	v_add_u32_e32 v15, 0xffffffb6, v0
	s_nop 0
	v_cndmask_b32_e32 v121, v235, v121, vcc
	v_cmp_le_i32_e32 vcc, v15, v246
	v_add_u32_e32 v15, 0xffffff97, v0
	s_nop 0
	v_cndmask_b32_e32 v137, v235, v137, vcc
	v_cmp_le_i32_e32 vcc, v15, v246
	v_add_u32_e32 v15, 0xffffffb7, v0
	s_nop 0
	v_cndmask_b32_e32 v122, v235, v122, vcc
	v_cmp_le_i32_e32 vcc, v15, v246
	v_add_u32_e32 v15, 0xffffff98, v0
	s_nop 0
	v_cndmask_b32_e32 v138, v235, v138, vcc
	v_cmp_le_i32_e32 vcc, v15, v246
	v_add_u32_e32 v15, 0xffffffb8, v0
	s_nop 0
	v_cndmask_b32_e32 v123, v235, v123, vcc
	v_cmp_le_i32_e32 vcc, v15, v246
	v_add_u32_e32 v15, 0xffffff9d, v0
	s_nop 0
	v_cndmask_b32_e32 v139, v235, v139, vcc
	v_cmp_le_i32_e32 vcc, v15, v246
	v_add_u32_e32 v15, 0xffffffbd, v0
	s_nop 0
	v_cndmask_b32_e32 v124, v235, v124, vcc
	v_cmp_le_i32_e32 vcc, v15, v246
	v_add_u32_e32 v15, 0xffffff9e, v0
	s_nop 0
	v_cndmask_b32_e32 v140, v235, v140, vcc
	v_cmp_le_i32_e32 vcc, v15, v246
	v_add_u32_e32 v15, 0xffffffbe, v0
	s_nop 0
	v_cndmask_b32_e32 v125, v235, v125, vcc
	v_cmp_le_i32_e32 vcc, v15, v246
	v_add_u32_e32 v15, 0xffffff9f, v0
	s_nop 0
	v_cndmask_b32_e32 v141, v235, v141, vcc
	v_cmp_le_i32_e32 vcc, v15, v246
	v_add_u32_e32 v15, 0xffffffbf, v0
	s_nop 0
	v_cndmask_b32_e32 v126, v235, v126, vcc
	v_cmp_le_i32_e32 vcc, v15, v246
	v_add_u32_e32 v15, 0xffffffa0, v0
	s_nop 0
	v_cndmask_b32_e32 v142, v235, v142, vcc
	v_cmp_le_i32_e32 vcc, v15, v246
	v_subrev_u32_e32 v15, 64, v0
	s_nop 0
	v_cndmask_b32_e32 v127, v235, v127, vcc
	v_cmp_le_i32_e32 vcc, v15, v246
	s_nop 1
	v_cndmask_b32_e32 v143, v235, v143, vcc

; __device__ __forceinline__ void biasd(f32x16&p0,f32x16&p1,const __attribute__((address_space(3))) float*lut,int base){
;   #pragma unroll
;   for(int r=0;r<16;++r){ const int d0=base-((r&3)+8*(r>>2)); unsigned i0=(unsigned)d0; i0=i0>127u?127u:i0; unsigned i1=(unsigned)(d0-32); i1=i1>127u?127u:i1; p0[r]+=lut[i0]; p1[r]+=lut[i1];
;     if((r&3)==3){ asm volatile("":"+v"(p0),"+v"(p1)); __builtin_amdgcn_sched_barrier(0); } }
; }
.LBB0_501:
	v_add_u32_e32 v15, v238, v252
	v_add_u32_e32 v80, -64, v15
	v_cmp_gt_u32_e32 vcc, 0xba, v80
	s_cbranch_vccnz .Lbias_full_l0b
	s_add_i32 s40, s40, 1
	s_waitcnt lgkmcnt(0)
	s_branch .Lbias_end_l0b
.Lbias_full_l0b:
	v_add_u32_e32 v82, 0xffffffbf, v15
	v_min_u32_e32 v82, 0x7f, v82
	v_lshl_add_u32 v84, v82, 2, s89
	v_add_u32_e32 v82, 0xffffffbe, v15
	v_subrev_u32_e32 v80, 64, v15
	v_add_u32_e32 v81, 0xffffffa0, v15
	v_add_u32_e32 v83, 0xffffff9f, v15
	v_min_u32_e32 v82, 0x7f, v82
	v_add_u32_e32 v85, 0xffffff9e, v15
	v_add_u32_e32 v87, 0xffffff9d, v15
	v_min_u32_e32 v80, 0x7f, v80
	v_min_u32_e32 v81, 0x7f, v81
	v_min_u32_e32 v83, 0x7f, v83
	v_min_u32_e32 v85, 0x7f, v85
	v_lshl_add_u32 v86, v82, 2, s89
	v_add_u32_e32 v82, 0xffffffbd, v15
	v_min_u32_e32 v87, 0x7f, v87
	v_lshl_add_u32 v80, v80, 2, s89
	v_lshl_add_u32 v81, v81, 2, s89
	v_lshl_add_u32 v83, v83, 2, s89
	v_lshl_add_u32 v85, v85, 2, s89
	v_min_u32_e32 v82, 0x7f, v82
	v_lshl_add_u32 v87, v87, 2, s89
	v_lshl_add_u32 v88, v82, 2, s89
	ds_read_b32 v80, v80
	ds_read_b32 v82, v81
	ds_read_b32 v81, v84
	ds_read_b32 v83, v83
	ds_read_b32 v84, v86
	ds_read_b32 v86, v85
	ds_read_b32 v85, v88
	ds_read_b32 v87, v87
	s_waitcnt lgkmcnt(5)
	v_pk_add_f32 v[112:113], v[112:113], v[80:81]
	s_waitcnt lgkmcnt(4)
	v_pk_add_f32 v[128:129], v[128:129], v[82:83]
	s_add_i32 s40, s40, 1
	s_waitcnt lgkmcnt(1)
	v_pk_add_f32 v[114:115], v[114:115], v[84:85]
	s_waitcnt lgkmcnt(0)
	v_pk_add_f32 v[130:131], v[130:131], v[86:87]
	s_nop 0
	v_add_u32_e32 v82, 0xffffffb7, v15
	v_min_u32_e32 v82, 0x7f, v82
	v_lshl_add_u32 v84, v82, 2, s89
	v_add_u32_e32 v82, 0xffffffb6, v15
	v_add_u32_e32 v80, 0xffffffb8, v15
	v_add_u32_e32 v81, 0xffffff98, v15
	v_add_u32_e32 v83, 0xffffff97, v15
	v_min_u32_e32 v82, 0x7f, v82
	v_add_u32_e32 v85, 0xffffff96, v15
	v_add_u32_e32 v87, 0xffffff95, v15
	v_min_u32_e32 v80, 0x7f, v80
	v_min_u32_e32 v81, 0x7f, v81
	v_min_u32_e32 v83, 0x7f, v83
	v_min_u32_e32 v85, 0x7f, v85
	v_lshl_add_u32 v86, v82, 2, s89
	v_add_u32_e32 v82, 0xffffffb5, v15
	v_min_u32_e32 v87, 0x7f, v87
	v_lshl_add_u32 v80, v80, 2, s89
	v_lshl_add_u32 v81, v81, 2, s89
	v_lshl_add_u32 v83, v83, 2, s89
	v_lshl_add_u32 v85, v85, 2, s89
	v_min_u32_e32 v82, 0x7f, v82
	v_lshl_add_u32 v87, v87, 2, s89
	v_lshl_add_u32 v88, v82, 2, s89
	ds_read_b32 v80, v80
	ds_read_b32 v82, v81
	ds_read_b32 v81, v84
	ds_read_b32 v83, v83
	ds_read_b32 v84, v86
	ds_read_b32 v86, v85
	ds_read_b32 v85, v88
	ds_read_b32 v87, v87
	s_waitcnt lgkmcnt(5)
	v_pk_add_f32 v[116:117], v[80:81], v[116:117]
	s_waitcnt lgkmcnt(4)
	v_pk_add_f32 v[132:133], v[132:133], v[82:83]
	s_waitcnt lgkmcnt(1)
	v_pk_add_f32 v[118:119], v[118:119], v[84:85]
	s_waitcnt lgkmcnt(0)
	v_pk_add_f32 v[134:135], v[134:135], v[86:87]
	s_nop 0
	v_add_u32_e32 v82, 0xffffffaf, v15
	v_min_u32_e32 v82, 0x7f, v82
	v_lshl_add_u32 v84, v82, 2, s89
	v_add_u32_e32 v82, 0xffffffae, v15
	v_add_u32_e32 v80, 0xffffffb0, v15
	v_add_u32_e32 v81, 0xffffff90, v15
	v_add_u32_e32 v83, 0xffffff8f, v15
	v_min_u32_e32 v82, 0x7f, v82
	v_add_u32_e32 v85, 0xffffff8e, v15
	v_add_u32_e32 v87, 0xffffff8d, v15
	v_min_u32_e32 v80, 0x7f, v80
	v_min_u32_e32 v81, 0x7f, v81
	v_min_u32_e32 v83, 0x7f, v83
	v_min_u32_e32 v85, 0x7f, v85
	v_lshl_add_u32 v86, v82, 2, s89
	v_add_u32_e32 v82, 0xffffffad, v15
	v_min_u32_e32 v87, 0x7f, v87
	v_lshl_add_u32 v80, v80, 2, s89
	v_lshl_add_u32 v81, v81, 2, s89
	v_lshl_add_u32 v83, v83, 2, s89
	v_lshl_add_u32 v85, v85, 2, s89
	v_min_u32_e32 v82, 0x7f, v82
	v_lshl_add_u32 v87, v87, 2, s89
	v_lshl_add_u32 v88, v82, 2, s89
	ds_read_b32 v80, v80
	ds_read_b32 v82, v81
	ds_read_b32 v81, v84
	ds_read_b32 v83, v83
	ds_read_b32 v84, v86
	ds_read_b32 v86, v85
	ds_read_b32 v85, v88
	ds_read_b32 v87, v87
	s_waitcnt lgkmcnt(5)
	v_pk_add_f32 v[120:121], v[80:81], v[120:121]
	s_waitcnt lgkmcnt(4)
	v_pk_add_f32 v[136:137], v[136:137], v[82:83]
	s_waitcnt lgkmcnt(1)
	v_pk_add_f32 v[122:123], v[122:123], v[84:85]
	s_waitcnt lgkmcnt(0)
	v_pk_add_f32 v[138:139], v[138:139], v[86:87]
	s_nop 0
	v_add_u32_e32 v82, 0xffffffa7, v15
	v_min_u32_e32 v82, 0x7f, v82
	v_lshl_add_u32 v84, v82, 2, s89
	v_add_u32_e32 v82, 0xffffffa6, v15
	v_min_u32_e32 v82, 0x7f, v82
	v_add_u32_e32 v80, 0xffffffa8, v15
	v_add_u32_e32 v81, 0xffffff88, v15
	v_add_u32_e32 v83, 0xffffff87, v15
	v_add_u32_e32 v85, 0xffffff86, v15
	v_lshl_add_u32 v86, v82, 2, s89
	v_add_u32_e32 v82, 0xffffffa5, v15
	v_min_u32_e32 v80, 0x7f, v80
	v_min_u32_e32 v81, 0x7f, v81
	v_min_u32_e32 v83, 0x7f, v83
	v_min_u32_e32 v85, 0x7f, v85
	v_min_u32_e32 v82, 0x7f, v82
	v_add_u32_e32 v15, 0xffffff85, v15
	v_lshl_add_u32 v80, v80, 2, s89
	v_lshl_add_u32 v81, v81, 2, s89
	v_lshl_add_u32 v83, v83, 2, s89
	v_lshl_add_u32 v85, v85, 2, s89
	v_min_u32_e32 v15, 0x7f, v15
	v_lshl_add_u32 v87, v82, 2, s89
	v_lshl_add_u32 v15, v15, 2, s89
	ds_read_b32 v80, v80
	ds_read_b32 v82, v81
	ds_read_b32 v81, v84
	ds_read_b32 v83, v83
	ds_read_b32 v84, v86
	ds_read_b32 v86, v85
	ds_read_b32 v85, v87
	ds_read_b32 v87, v15
	s_waitcnt lgkmcnt(5)
	v_pk_add_f32 v[124:125], v[80:81], v[124:125]
	s_waitcnt lgkmcnt(4)
	v_pk_add_f32 v[140:141], v[140:141], v[82:83]
	s_waitcnt lgkmcnt(1)
	v_pk_add_f32 v[126:127], v[126:127], v[84:85]
	s_waitcnt lgkmcnt(0)
	v_pk_add_f32 v[142:143], v[142:143], v[86:87]
	s_nop 0
; __device__ __forceinline__ void cmask(f32x16&p0,f32x16&p1,int jb,int qrel,int hi){
;   const float NEG=-INFINITY; int kb=64*jb+4*hi;
;   #pragma unroll
;   for(int r=0;r<16;++r){int kv=kb+(r&3)+8*(r>>2); if(kv>qrel)p0[r]=NEG; if(kv+32>qrel)p1[r]=NEG;}
; }
.Lbias_end_l0b:
	s_cmp_lt_i32 s40, 0
	s_cbranch_scc1 .LBB0_503
	v_subrev_u32_e32 v80, 27, v0
	v_subrev_u32_e32 v15, 59, v0
	v_cmp_le_i32_e32 vcc, v80, v246
	s_nop 1
	v_cndmask_b32_e32 v128, v235, v128, vcc
	v_cmp_lt_i32_e32 vcc, v15, v246
	s_nop 1
	v_cndmask_b32_e32 v113, v235, v113, vcc
	v_cmp_le_i32_e32 vcc, v15, v246
	v_subrev_u32_e32 v15, 26, v0
	s_nop 0
	v_cndmask_b32_e32 v112, v235, v112, vcc
	v_cmp_le_i32_e32 vcc, v15, v246
	v_subrev_u32_e32 v15, 57, v0
	s_nop 0
	v_cndmask_b32_e32 v129, v235, v129, vcc
	v_cmp_le_i32_e32 vcc, v15, v246
	v_subrev_u32_e32 v15, 25, v0
	s_nop 0
	v_cndmask_b32_e32 v114, v235, v114, vcc
	v_cmp_le_i32_e32 vcc, v15, v246
	v_subrev_u32_e32 v15, 56, v0
	s_nop 0
	v_cndmask_b32_e32 v130, v235, v130, vcc
	v_cmp_le_i32_e32 vcc, v15, v246
	v_subrev_u32_e32 v15, 24, v0
	s_nop 0
	v_cndmask_b32_e32 v115, v235, v115, vcc
	v_cmp_le_i32_e32 vcc, v15, v246
	v_subrev_u32_e32 v15, 51, v0
	s_nop 0
	v_cndmask_b32_e32 v131, v235, v131, vcc
	v_cmp_le_i32_e32 vcc, v15, v246
	v_subrev_u32_e32 v15, 19, v0
	s_nop 0
	v_cndmask_b32_e32 v116, v235, v116, vcc
	v_cmp_le_i32_e32 vcc, v15, v246
	v_subrev_u32_e32 v15, 50, v0
	s_nop 0
	v_cndmask_b32_e32 v132, v235, v132, vcc
	v_cmp_le_i32_e32 vcc, v15, v246
	v_subrev_u32_e32 v15, 18, v0
	s_nop 0
	v_cndmask_b32_e32 v117, v235, v117, vcc
	v_cmp_le_i32_e32 vcc, v15, v246
	v_subrev_u32_e32 v15, 49, v0
	s_nop 0
	v_cndmask_b32_e32 v133, v235, v133, vcc
	v_cmp_le_i32_e32 vcc, v15, v246
	v_subrev_u32_e32 v15, 17, v0
	s_nop 0
	v_cndmask_b32_e32 v118, v235, v118, vcc
	v_cmp_le_i32_e32 vcc, v15, v246
	v_subrev_u32_e32 v15, 48, v0
	s_nop 0
	v_cndmask_b32_e32 v134, v235, v134, vcc
	v_cmp_le_i32_e32 vcc, v15, v246
	v_add_u32_e32 v15, -16, v0
	s_nop 0
	v_cndmask_b32_e32 v119, v235, v119, vcc
	v_cmp_le_i32_e32 vcc, v15, v246
	v_subrev_u32_e32 v15, 43, v0
	s_nop 0
	v_cndmask_b32_e32 v135, v235, v135, vcc
	v_cmp_le_i32_e32 vcc, v15, v246
	v_add_u32_e32 v15, -11, v0
	s_nop 0
	v_cndmask_b32_e32 v120, v235, v120, vcc
	v_cmp_le_i32_e32 vcc, v15, v246
	v_subrev_u32_e32 v15, 42, v0
	s_nop 0
	v_cndmask_b32_e32 v136, v235, v136, vcc
	v_cmp_le_i32_e32 vcc, v15, v246
	v_add_u32_e32 v15, -10, v0
	s_nop 0
	v_cndmask_b32_e32 v121, v235, v121, vcc
	v_cmp_le_i32_e32 vcc, v15, v246
	v_subrev_u32_e32 v15, 41, v0
	s_nop 0
	v_cndmask_b32_e32 v137, v235, v137, vcc
	v_cmp_le_i32_e32 vcc, v15, v246
	v_add_u32_e32 v15, -9, v0
	s_nop 0
	v_cndmask_b32_e32 v122, v235, v122, vcc
	v_cmp_le_i32_e32 vcc, v15, v246
	v_subrev_u32_e32 v15, 40, v0
	s_nop 0
	v_cndmask_b32_e32 v138, v235, v138, vcc
	v_cmp_le_i32_e32 vcc, v15, v246
	v_add_u32_e32 v15, -8, v0
	s_nop 0
	v_cndmask_b32_e32 v123, v235, v123, vcc
	v_cmp_le_i32_e32 vcc, v15, v246
	v_subrev_u32_e32 v15, 35, v0
	s_nop 0
	v_cndmask_b32_e32 v139, v235, v139, vcc
	v_cmp_le_i32_e32 vcc, v15, v246
	v_add_u32_e32 v15, -3, v0
	s_nop 0
	v_cndmask_b32_e32 v124, v235, v124, vcc
	v_cmp_le_i32_e32 vcc, v15, v246
	v_subrev_u32_e32 v15, 34, v0
	s_nop 0
	v_cndmask_b32_e32 v140, v235, v140, vcc
	v_cmp_le_i32_e32 vcc, v15, v246
	v_add_u32_e32 v15, -2, v0
	s_nop 0
	v_cndmask_b32_e32 v125, v235, v125, vcc
	v_cmp_le_i32_e32 vcc, v15, v246
	v_subrev_u32_e32 v15, 33, v0
	s_nop 0
	v_cndmask_b32_e32 v141, v235, v141, vcc
	v_cmp_le_i32_e32 vcc, v15, v246
	v_add_u32_e32 v15, -1, v0
	s_nop 0
	v_cndmask_b32_e32 v126, v235, v126, vcc
	v_cmp_le_i32_e32 vcc, v15, v246
	v_subrev_u32_e32 v15, 32, v0
	s_nop 0
	v_cndmask_b32_e32 v142, v235, v142, vcc
	v_cmp_le_i32_e32 vcc, v15, v246
	s_nop 1
	v_cndmask_b32_e32 v127, v235, v127, vcc
	v_cmp_le_i32_e32 vcc, v0, v246
	s_nop 1
	v_cndmask_b32_e32 v143, v235, v143, vcc

; __device__ __forceinline__ void biasd(f32x16&p0,f32x16&p1,const __attribute__((address_space(3))) float*lut,int base){
;   #pragma unroll
;   for(int r=0;r<16;++r){ const int d0=base-((r&3)+8*(r>>2)); unsigned i0=(unsigned)d0; i0=i0>127u?127u:i0; unsigned i1=(unsigned)(d0-32); i1=i1>127u?127u:i1; p0[r]+=lut[i0]; p1[r]+=lut[i1];
;     if((r&3)==3){ asm volatile("":"+v"(p0),"+v"(p1)); __builtin_amdgcn_sched_barrier(0); } }
; }
.LBB0_1530:
	v_add_u32_e32 v15, v237, v252
	v_cmp_gt_u32_e32 vcc, 0xba, v15
	s_cbranch_vccnz .Lbias_full_l1a
	s_add_i32 s10, s48, 1
	s_lshl_b32 s90, s88, 1
	s_lshl_b32 s10, s10, 14
	s_add_i32 s11, s90, s67
	s_mov_b32 s44, m0
	s_mov_b32 m0, s11
	s_nop 0
	buffer_load_dwordx4 v247, s[16:19], s10 offen lds
	s_mov_b32 m0, s44
	s_bitset1_b32 s10, 7
	s_add_i32 s11, s90, s53
	s_mov_b32 s44, m0
	s_mov_b32 m0, s11
	s_nop 0
	buffer_load_dwordx4 v247, s[16:19], s10 offen lds
	s_mov_b32 m0, s44
	s_add_i32 s49, s89, s48
	s_waitcnt lgkmcnt(0)
	s_branch .Lbias_end_l1a
.Lbias_full_l1a:
	v_add_u32_e32 v82, -1, v15
	v_min_u32_e32 v82, 0x7f, v82
	v_lshl_add_u32 v84, v82, 2, s85
	v_add_u32_e32 v82, -2, v15
	s_add_i32 s10, s48, 1
	s_lshl_b32 s90, s88, 1
	v_subrev_u32_e32 v81, 32, v15
	v_subrev_u32_e32 v83, 33, v15
	v_min_u32_e32 v82, 0x7f, v82
	v_subrev_u32_e32 v85, 34, v15
	v_subrev_u32_e32 v87, 35, v15
	s_lshl_b32 s10, s10, 14
	s_add_i32 s11, s90, s67
	s_mov_b32 s44, m0
	s_mov_b32 m0, s11
	s_nop 0
	buffer_load_dwordx4 v247, s[16:19], s10 offen lds
	s_mov_b32 m0, s44
	v_min_u32_e32 v80, 0x7f, v15
	v_min_u32_e32 v81, 0x7f, v81
	v_min_u32_e32 v83, 0x7f, v83
	v_min_u32_e32 v85, 0x7f, v85
	v_lshl_add_u32 v86, v82, 2, s85
	v_add_u32_e32 v82, -3, v15
	v_min_u32_e32 v87, 0x7f, v87
	s_bitset1_b32 s10, 7
	s_add_i32 s11, s90, s53
	s_mov_b32 s44, m0
	s_mov_b32 m0, s11
	s_nop 0
	buffer_load_dwordx4 v247, s[16:19], s10 offen lds
	s_mov_b32 m0, s44
	v_lshl_add_u32 v80, v80, 2, s85
	v_lshl_add_u32 v81, v81, 2, s85
	v_lshl_add_u32 v83, v83, 2, s85
	v_lshl_add_u32 v85, v85, 2, s85
	v_min_u32_e32 v82, 0x7f, v82
	v_lshl_add_u32 v87, v87, 2, s85
	v_lshl_add_u32 v88, v82, 2, s85
	ds_read_b32 v80, v80
	ds_read_b32 v82, v81
	ds_read_b32 v81, v84
	ds_read_b32 v83, v83
	ds_read_b32 v84, v86
	ds_read_b32 v86, v85
	ds_read_b32 v85, v88
	ds_read_b32 v87, v87
	s_add_i32 s49, s89, s48
	s_waitcnt lgkmcnt(5)
	v_pk_add_f32 v[112:113], v[112:113], v[80:81]
	s_waitcnt lgkmcnt(4)
	v_pk_add_f32 v[128:129], v[128:129], v[82:83]
	s_waitcnt lgkmcnt(1)
	v_pk_add_f32 v[114:115], v[114:115], v[84:85]
	s_waitcnt lgkmcnt(0)
	v_pk_add_f32 v[130:131], v[130:131], v[86:87]
	s_nop 0
	v_add_u32_e32 v82, -9, v15
	v_min_u32_e32 v82, 0x7f, v82
	v_lshl_add_u32 v84, v82, 2, s85
	v_add_u32_e32 v82, -10, v15
	v_add_u32_e32 v80, -8, v15
	v_subrev_u32_e32 v81, 40, v15
	v_subrev_u32_e32 v83, 41, v15
	v_min_u32_e32 v82, 0x7f, v82
	v_subrev_u32_e32 v85, 42, v15
	v_subrev_u32_e32 v87, 43, v15
	v_min_u32_e32 v80, 0x7f, v80
	v_min_u32_e32 v81, 0x7f, v81
	v_min_u32_e32 v83, 0x7f, v83
	v_min_u32_e32 v85, 0x7f, v85
	v_lshl_add_u32 v86, v82, 2, s85
	v_add_u32_e32 v82, -11, v15
	v_min_u32_e32 v87, 0x7f, v87
	v_lshl_add_u32 v80, v80, 2, s85
	v_lshl_add_u32 v81, v81, 2, s85
	v_lshl_add_u32 v83, v83, 2, s85
	v_lshl_add_u32 v85, v85, 2, s85
	v_min_u32_e32 v82, 0x7f, v82
	v_lshl_add_u32 v87, v87, 2, s85
	v_lshl_add_u32 v88, v82, 2, s85
	ds_read_b32 v80, v80
	ds_read_b32 v82, v81
	ds_read_b32 v81, v84
	ds_read_b32 v83, v83
	ds_read_b32 v84, v86
	ds_read_b32 v86, v85
	ds_read_b32 v85, v88
	ds_read_b32 v87, v87
	s_waitcnt lgkmcnt(5)
	v_pk_add_f32 v[116:117], v[80:81], v[116:117]
	s_waitcnt lgkmcnt(4)
	v_pk_add_f32 v[132:133], v[132:133], v[82:83]
	s_waitcnt lgkmcnt(1)
	v_pk_add_f32 v[118:119], v[118:119], v[84:85]
	s_waitcnt lgkmcnt(0)
	v_pk_add_f32 v[134:135], v[134:135], v[86:87]
	s_nop 0
	v_subrev_u32_e32 v82, 17, v15
	v_min_u32_e32 v82, 0x7f, v82
	v_lshl_add_u32 v84, v82, 2, s85
	v_subrev_u32_e32 v82, 18, v15
	v_add_u32_e32 v80, -16, v15
	v_subrev_u32_e32 v81, 48, v15
	v_subrev_u32_e32 v83, 49, v15
	v_min_u32_e32 v82, 0x7f, v82
	v_subrev_u32_e32 v85, 50, v15
	v_subrev_u32_e32 v87, 51, v15
	v_min_u32_e32 v80, 0x7f, v80
	v_min_u32_e32 v81, 0x7f, v81
	v_min_u32_e32 v83, 0x7f, v83
	v_min_u32_e32 v85, 0x7f, v85
	v_lshl_add_u32 v86, v82, 2, s85
	v_subrev_u32_e32 v82, 19, v15
	v_min_u32_e32 v87, 0x7f, v87
	v_lshl_add_u32 v80, v80, 2, s85
	v_lshl_add_u32 v81, v81, 2, s85
	v_lshl_add_u32 v83, v83, 2, s85
	v_lshl_add_u32 v85, v85, 2, s85
	v_min_u32_e32 v82, 0x7f, v82
	v_lshl_add_u32 v87, v87, 2, s85
	v_lshl_add_u32 v88, v82, 2, s85
	ds_read_b32 v80, v80
	ds_read_b32 v82, v81
	ds_read_b32 v81, v84
	ds_read_b32 v83, v83
	ds_read_b32 v84, v86
	ds_read_b32 v86, v85
	ds_read_b32 v85, v88
	ds_read_b32 v87, v87
	s_waitcnt lgkmcnt(5)
	v_pk_add_f32 v[120:121], v[80:81], v[120:121]
	s_waitcnt lgkmcnt(4)
	v_pk_add_f32 v[136:137], v[136:137], v[82:83]
	s_waitcnt lgkmcnt(1)
	v_pk_add_f32 v[122:123], v[122:123], v[84:85]
	s_waitcnt lgkmcnt(0)
	v_pk_add_f32 v[138:139], v[138:139], v[86:87]
	s_nop 0
	v_subrev_u32_e32 v82, 25, v15
	v_min_u32_e32 v82, 0x7f, v82
	v_lshl_add_u32 v84, v82, 2, s85
	v_subrev_u32_e32 v82, 26, v15
	v_min_u32_e32 v82, 0x7f, v82
	v_subrev_u32_e32 v80, 24, v15
	v_subrev_u32_e32 v81, 56, v15
	v_subrev_u32_e32 v83, 57, v15
	v_subrev_u32_e32 v85, 58, v15
	v_lshl_add_u32 v86, v82, 2, s85
	v_subrev_u32_e32 v82, 27, v15
	v_min_u32_e32 v80, 0x7f, v80
	v_min_u32_e32 v81, 0x7f, v81
	v_min_u32_e32 v83, 0x7f, v83
	v_min_u32_e32 v85, 0x7f, v85
	v_min_u32_e32 v82, 0x7f, v82
	v_subrev_u32_e32 v15, 59, v15
	v_lshl_add_u32 v80, v80, 2, s85
	v_lshl_add_u32 v81, v81, 2, s85
	v_lshl_add_u32 v83, v83, 2, s85
	v_lshl_add_u32 v85, v85, 2, s85
	v_min_u32_e32 v15, 0x7f, v15
	v_lshl_add_u32 v87, v82, 2, s85
	v_lshl_add_u32 v15, v15, 2, s85
	ds_read_b32 v80, v80
	ds_read_b32 v82, v81
	ds_read_b32 v81, v84
	ds_read_b32 v83, v83
	ds_read_b32 v84, v86
	ds_read_b32 v86, v85
	ds_read_b32 v85, v87
	ds_read_b32 v87, v15
	s_waitcnt lgkmcnt(5)
	v_pk_add_f32 v[124:125], v[80:81], v[124:125]
	s_waitcnt lgkmcnt(4)
	v_pk_add_f32 v[140:141], v[140:141], v[82:83]
	s_waitcnt lgkmcnt(1)
	v_pk_add_f32 v[126:127], v[126:127], v[84:85]
	s_waitcnt lgkmcnt(0)
	v_pk_add_f32 v[142:143], v[142:143], v[86:87]
	s_nop 0
; __device__ __forceinline__ void cmask(f32x16&p0,f32x16&p1,int jb,int qrel,int hi){
;   const float NEG=-INFINITY; int kb=64*jb+4*hi;
;   #pragma unroll
;   for(int r=0;r<16;++r){int kv=kb+(r&3)+8*(r>>2); if(kv>qrel)p0[r]=NEG; if(kv+32>qrel)p1[r]=NEG;}
; }
.Lbias_end_l1a:
	s_cmp_lt_i32 s49, 0
	s_cbranch_scc1 .LBB0_1532
	v_add_u32_e32 v80, 0xffffffa5, v0
	v_add_u32_e32 v15, 0xffffff85, v0
	v_cmp_le_i32_e32 vcc, v80, v245
	s_nop 1
	v_cndmask_b32_e32 v128, v234, v128, vcc
	v_cmp_lt_i32_e32 vcc, v15, v245
	s_nop 1
	v_cndmask_b32_e32 v113, v234, v113, vcc
	v_cmp_le_i32_e32 vcc, v15, v245
	v_add_u32_e32 v15, 0xffffffa6, v0
	s_nop 0
	v_cndmask_b32_e32 v112, v234, v112, vcc
	v_cmp_le_i32_e32 vcc, v15, v245
	v_add_u32_e32 v15, 0xffffff87, v0
	s_nop 0
	v_cndmask_b32_e32 v129, v234, v129, vcc
	v_cmp_le_i32_e32 vcc, v15, v245
	v_add_u32_e32 v15, 0xffffffa7, v0
	s_nop 0
	v_cndmask_b32_e32 v114, v234, v114, vcc
	v_cmp_le_i32_e32 vcc, v15, v245
	v_add_u32_e32 v15, 0xffffff88, v0
	s_nop 0
	v_cndmask_b32_e32 v130, v234, v130, vcc
	v_cmp_le_i32_e32 vcc, v15, v245
	v_add_u32_e32 v15, 0xffffffa8, v0
	s_nop 0
	v_cndmask_b32_e32 v115, v234, v115, vcc
	v_cmp_le_i32_e32 vcc, v15, v245
	v_add_u32_e32 v15, 0xffffff8d, v0
	s_nop 0
	v_cndmask_b32_e32 v131, v234, v131, vcc
	v_cmp_le_i32_e32 vcc, v15, v245
	v_add_u32_e32 v15, 0xffffffad, v0
	s_nop 0
	v_cndmask_b32_e32 v116, v234, v116, vcc
	v_cmp_le_i32_e32 vcc, v15, v245
	v_add_u32_e32 v15, 0xffffff8e, v0
	s_nop 0
	v_cndmask_b32_e32 v132, v234, v132, vcc
	v_cmp_le_i32_e32 vcc, v15, v245
	v_add_u32_e32 v15, 0xffffffae, v0
	s_nop 0
	v_cndmask_b32_e32 v117, v234, v117, vcc
	v_cmp_le_i32_e32 vcc, v15, v245
	v_add_u32_e32 v15, 0xffffff8f, v0
	s_nop 0
	v_cndmask_b32_e32 v133, v234, v133, vcc
	v_cmp_le_i32_e32 vcc, v15, v245
	v_add_u32_e32 v15, 0xffffffaf, v0
	s_nop 0
	v_cndmask_b32_e32 v118, v234, v118, vcc
	v_cmp_le_i32_e32 vcc, v15, v245
	v_add_u32_e32 v15, 0xffffff90, v0
	s_nop 0
	v_cndmask_b32_e32 v134, v234, v134, vcc
	v_cmp_le_i32_e32 vcc, v15, v245
	v_add_u32_e32 v15, 0xffffffb0, v0
	s_nop 0
	v_cndmask_b32_e32 v119, v234, v119, vcc
	v_cmp_le_i32_e32 vcc, v15, v245
	v_add_u32_e32 v15, 0xffffff95, v0
	s_nop 0
	v_cndmask_b32_e32 v135, v234, v135, vcc
	v_cmp_le_i32_e32 vcc, v15, v245
	v_add_u32_e32 v15, 0xffffffb5, v0
	s_nop 0
	v_cndmask_b32_e32 v120, v234, v120, vcc
	v_cmp_le_i32_e32 vcc, v15, v245
	v_add_u32_e32 v15, 0xffffff96, v0
	s_nop 0
	v_cndmask_b32_e32 v136, v234, v136, vcc
	v_cmp_le_i32_e32 vcc, v15, v245
	v_add_u32_e32 v15, 0xffffffb6, v0
	s_nop 0
	v_cndmask_b32_e32 v121, v234, v121, vcc
	v_cmp_le_i32_e32 vcc, v15, v245
	v_add_u32_e32 v15, 0xffffff97, v0
	s_nop 0
	v_cndmask_b32_e32 v137, v234, v137, vcc
	v_cmp_le_i32_e32 vcc, v15, v245
	v_add_u32_e32 v15, 0xffffffb7, v0
	s_nop 0
	v_cndmask_b32_e32 v122, v234, v122, vcc
	v_cmp_le_i32_e32 vcc, v15, v245
	v_add_u32_e32 v15, 0xffffff98, v0
	s_nop 0
	v_cndmask_b32_e32 v138, v234, v138, vcc
	v_cmp_le_i32_e32 vcc, v15, v245
	v_add_u32_e32 v15, 0xffffffb8, v0
	s_nop 0
	v_cndmask_b32_e32 v123, v234, v123, vcc
	v_cmp_le_i32_e32 vcc, v15, v245
	v_add_u32_e32 v15, 0xffffff9d, v0
	s_nop 0
	v_cndmask_b32_e32 v139, v234, v139, vcc
	v_cmp_le_i32_e32 vcc, v15, v245
	v_add_u32_e32 v15, 0xffffffbd, v0
	s_nop 0
	v_cndmask_b32_e32 v124, v234, v124, vcc
	v_cmp_le_i32_e32 vcc, v15, v245
	v_add_u32_e32 v15, 0xffffff9e, v0
	s_nop 0
	v_cndmask_b32_e32 v140, v234, v140, vcc
	v_cmp_le_i32_e32 vcc, v15, v245
	v_add_u32_e32 v15, 0xffffffbe, v0
	s_nop 0
	v_cndmask_b32_e32 v125, v234, v125, vcc
	v_cmp_le_i32_e32 vcc, v15, v245
	v_add_u32_e32 v15, 0xffffff9f, v0
	s_nop 0
	v_cndmask_b32_e32 v141, v234, v141, vcc
	v_cmp_le_i32_e32 vcc, v15, v245
	v_add_u32_e32 v15, 0xffffffbf, v0
	s_nop 0
	v_cndmask_b32_e32 v126, v234, v126, vcc
	v_cmp_le_i32_e32 vcc, v15, v245
	v_add_u32_e32 v15, 0xffffffa0, v0
	s_nop 0
	v_cndmask_b32_e32 v142, v234, v142, vcc
	v_cmp_le_i32_e32 vcc, v15, v245
	v_subrev_u32_e32 v15, 64, v0
	s_nop 0
	v_cndmask_b32_e32 v127, v234, v127, vcc
	v_cmp_le_i32_e32 vcc, v15, v245
	s_nop 1
	v_cndmask_b32_e32 v143, v234, v143, vcc

; __device__ __forceinline__ void biasd(f32x16&p0,f32x16&p1,const __attribute__((address_space(3))) float*lut,int base){
;   #pragma unroll
;   for(int r=0;r<16;++r){ const int d0=base-((r&3)+8*(r>>2)); unsigned i0=(unsigned)d0; i0=i0>127u?127u:i0; unsigned i1=(unsigned)(d0-32); i1=i1>127u?127u:i1; p0[r]+=lut[i0]; p1[r]+=lut[i1];
;     if((r&3)==3){ asm volatile("":"+v"(p0),"+v"(p1)); __builtin_amdgcn_sched_barrier(0); } }
; }
.LBB0_1541:
	v_add_u32_e32 v15, v237, v251
	v_add_u32_e32 v80, -64, v15
	v_cmp_gt_u32_e32 vcc, 0xba, v80
	s_cbranch_vccnz .Lbias_full_l1b
	s_add_i32 s49, s49, 1
	s_waitcnt lgkmcnt(0)
	s_branch .Lbias_end_l1b
.Lbias_full_l1b:
	v_add_u32_e32 v82, 0xffffffbf, v15
	v_min_u32_e32 v82, 0x7f, v82
	v_lshl_add_u32 v84, v82, 2, s85
	v_add_u32_e32 v82, 0xffffffbe, v15
	v_subrev_u32_e32 v80, 64, v15
	v_add_u32_e32 v81, 0xffffffa0, v15
	v_add_u32_e32 v83, 0xffffff9f, v15
	v_min_u32_e32 v82, 0x7f, v82
	v_add_u32_e32 v85, 0xffffff9e, v15
	v_add_u32_e32 v87, 0xffffff9d, v15
	v_min_u32_e32 v80, 0x7f, v80
	v_min_u32_e32 v81, 0x7f, v81
	v_min_u32_e32 v83, 0x7f, v83
	v_min_u32_e32 v85, 0x7f, v85
	v_lshl_add_u32 v86, v82, 2, s85
	v_add_u32_e32 v82, 0xffffffbd, v15
	v_min_u32_e32 v87, 0x7f, v87
	v_lshl_add_u32 v80, v80, 2, s85
	v_lshl_add_u32 v81, v81, 2, s85
	v_lshl_add_u32 v83, v83, 2, s85
	v_lshl_add_u32 v85, v85, 2, s85
	v_min_u32_e32 v82, 0x7f, v82
	v_lshl_add_u32 v87, v87, 2, s85
	v_lshl_add_u32 v88, v82, 2, s85
	ds_read_b32 v80, v80
	ds_read_b32 v82, v81
	ds_read_b32 v81, v84
	ds_read_b32 v83, v83
	ds_read_b32 v84, v86
	ds_read_b32 v86, v85
	ds_read_b32 v85, v88
	ds_read_b32 v87, v87
	s_waitcnt lgkmcnt(5)
	v_pk_add_f32 v[112:113], v[112:113], v[80:81]
	s_waitcnt lgkmcnt(4)
	v_pk_add_f32 v[128:129], v[128:129], v[82:83]
	s_add_i32 s49, s49, 1
	s_waitcnt lgkmcnt(1)
	v_pk_add_f32 v[114:115], v[114:115], v[84:85]
	s_waitcnt lgkmcnt(0)
	v_pk_add_f32 v[130:131], v[130:131], v[86:87]
	s_nop 0
	v_add_u32_e32 v82, 0xffffffb7, v15
	v_min_u32_e32 v82, 0x7f, v82
	v_lshl_add_u32 v84, v82, 2, s85
	v_add_u32_e32 v82, 0xffffffb6, v15
	v_add_u32_e32 v80, 0xffffffb8, v15
	v_add_u32_e32 v81, 0xffffff98, v15
	v_add_u32_e32 v83, 0xffffff97, v15
	v_min_u32_e32 v82, 0x7f, v82
	v_add_u32_e32 v85, 0xffffff96, v15
	v_add_u32_e32 v87, 0xffffff95, v15
	v_min_u32_e32 v80, 0x7f, v80
	v_min_u32_e32 v81, 0x7f, v81
	v_min_u32_e32 v83, 0x7f, v83
	v_min_u32_e32 v85, 0x7f, v85
	v_lshl_add_u32 v86, v82, 2, s85
	v_add_u32_e32 v82, 0xffffffb5, v15
	v_min_u32_e32 v87, 0x7f, v87
	v_lshl_add_u32 v80, v80, 2, s85
	v_lshl_add_u32 v81, v81, 2, s85
	v_lshl_add_u32 v83, v83, 2, s85
	v_lshl_add_u32 v85, v85, 2, s85
	v_min_u32_e32 v82, 0x7f, v82
	v_lshl_add_u32 v87, v87, 2, s85
	v_lshl_add_u32 v88, v82, 2, s85
	ds_read_b32 v80, v80
	ds_read_b32 v82, v81
	ds_read_b32 v81, v84
	ds_read_b32 v83, v83
	ds_read_b32 v84, v86
	ds_read_b32 v86, v85
	ds_read_b32 v85, v88
	ds_read_b32 v87, v87
	s_waitcnt lgkmcnt(5)
	v_pk_add_f32 v[116:117], v[80:81], v[116:117]
	s_waitcnt lgkmcnt(4)
	v_pk_add_f32 v[132:133], v[132:133], v[82:83]
	s_waitcnt lgkmcnt(1)
	v_pk_add_f32 v[118:119], v[118:119], v[84:85]
	s_waitcnt lgkmcnt(0)
	v_pk_add_f32 v[134:135], v[134:135], v[86:87]
	s_nop 0
	v_add_u32_e32 v82, 0xffffffaf, v15
	v_min_u32_e32 v82, 0x7f, v82
	v_lshl_add_u32 v84, v82, 2, s85
	v_add_u32_e32 v82, 0xffffffae, v15
	v_add_u32_e32 v80, 0xffffffb0, v15
	v_add_u32_e32 v81, 0xffffff90, v15
	v_add_u32_e32 v83, 0xffffff8f, v15
	v_min_u32_e32 v82, 0x7f, v82
	v_add_u32_e32 v85, 0xffffff8e, v15
	v_add_u32_e32 v87, 0xffffff8d, v15
	v_min_u32_e32 v80, 0x7f, v80
	v_min_u32_e32 v81, 0x7f, v81
	v_min_u32_e32 v83, 0x7f, v83
	v_min_u32_e32 v85, 0x7f, v85
	v_lshl_add_u32 v86, v82, 2, s85
	v_add_u32_e32 v82, 0xffffffad, v15
	v_min_u32_e32 v87, 0x7f, v87
	v_lshl_add_u32 v80, v80, 2, s85
	v_lshl_add_u32 v81, v81, 2, s85
	v_lshl_add_u32 v83, v83, 2, s85
	v_lshl_add_u32 v85, v85, 2, s85
	v_min_u32_e32 v82, 0x7f, v82
	v_lshl_add_u32 v87, v87, 2, s85
	v_lshl_add_u32 v88, v82, 2, s85
	ds_read_b32 v80, v80
	ds_read_b32 v82, v81
	ds_read_b32 v81, v84
	ds_read_b32 v83, v83
	ds_read_b32 v84, v86
	ds_read_b32 v86, v85
	ds_read_b32 v85, v88
	ds_read_b32 v87, v87
	s_waitcnt lgkmcnt(5)
	v_pk_add_f32 v[120:121], v[80:81], v[120:121]
	s_waitcnt lgkmcnt(4)
	v_pk_add_f32 v[136:137], v[136:137], v[82:83]
	s_waitcnt lgkmcnt(1)
	v_pk_add_f32 v[122:123], v[122:123], v[84:85]
	s_waitcnt lgkmcnt(0)
	v_pk_add_f32 v[138:139], v[138:139], v[86:87]
	s_nop 0
	v_add_u32_e32 v82, 0xffffffa7, v15
	v_min_u32_e32 v82, 0x7f, v82
	v_lshl_add_u32 v84, v82, 2, s85
	v_add_u32_e32 v82, 0xffffffa6, v15
	v_min_u32_e32 v82, 0x7f, v82
	v_add_u32_e32 v80, 0xffffffa8, v15
	v_add_u32_e32 v81, 0xffffff88, v15
	v_add_u32_e32 v83, 0xffffff87, v15
	v_add_u32_e32 v85, 0xffffff86, v15
	v_lshl_add_u32 v86, v82, 2, s85
	v_add_u32_e32 v82, 0xffffffa5, v15
	v_min_u32_e32 v80, 0x7f, v80
	v_min_u32_e32 v81, 0x7f, v81
	v_min_u32_e32 v83, 0x7f, v83
	v_min_u32_e32 v85, 0x7f, v85
	v_min_u32_e32 v82, 0x7f, v82
	v_add_u32_e32 v15, 0xffffff85, v15
	v_lshl_add_u32 v80, v80, 2, s85
	v_lshl_add_u32 v81, v81, 2, s85
	v_lshl_add_u32 v83, v83, 2, s85
	v_lshl_add_u32 v85, v85, 2, s85
	v_min_u32_e32 v15, 0x7f, v15
	v_lshl_add_u32 v87, v82, 2, s85
	v_lshl_add_u32 v15, v15, 2, s85
	ds_read_b32 v80, v80
	ds_read_b32 v82, v81
	ds_read_b32 v81, v84
	ds_read_b32 v83, v83
	ds_read_b32 v84, v86
	ds_read_b32 v86, v85
	ds_read_b32 v85, v87
	ds_read_b32 v87, v15
	s_waitcnt lgkmcnt(5)
	v_pk_add_f32 v[124:125], v[80:81], v[124:125]
	s_waitcnt lgkmcnt(4)
	v_pk_add_f32 v[140:141], v[140:141], v[82:83]
	s_waitcnt lgkmcnt(1)
	v_pk_add_f32 v[126:127], v[126:127], v[84:85]
	s_waitcnt lgkmcnt(0)
	v_pk_add_f32 v[142:143], v[142:143], v[86:87]
	s_nop 0
; __device__ __forceinline__ void cmask(f32x16&p0,f32x16&p1,int jb,int qrel,int hi){
;   const float NEG=-INFINITY; int kb=64*jb+4*hi;
;   #pragma unroll
;   for(int r=0;r<16;++r){int kv=kb+(r&3)+8*(r>>2); if(kv>qrel)p0[r]=NEG; if(kv+32>qrel)p1[r]=NEG;}
; }
.Lbias_end_l1b:
	s_cmp_lt_i32 s49, 0
	s_cbranch_scc1 .LBB0_1543
	v_subrev_u32_e32 v80, 27, v0
	v_subrev_u32_e32 v15, 59, v0
	v_cmp_le_i32_e32 vcc, v80, v245
	s_nop 1
	v_cndmask_b32_e32 v128, v234, v128, vcc
	v_cmp_lt_i32_e32 vcc, v15, v245
	s_nop 1
	v_cndmask_b32_e32 v113, v234, v113, vcc
	v_cmp_le_i32_e32 vcc, v15, v245
	v_subrev_u32_e32 v15, 26, v0
	s_nop 0
	v_cndmask_b32_e32 v112, v234, v112, vcc
	v_cmp_le_i32_e32 vcc, v15, v245
	v_subrev_u32_e32 v15, 57, v0
	s_nop 0
	v_cndmask_b32_e32 v129, v234, v129, vcc
	v_cmp_le_i32_e32 vcc, v15, v245
	v_subrev_u32_e32 v15, 25, v0
	s_nop 0
	v_cndmask_b32_e32 v114, v234, v114, vcc
	v_cmp_le_i32_e32 vcc, v15, v245
	v_subrev_u32_e32 v15, 56, v0
	s_nop 0
	v_cndmask_b32_e32 v130, v234, v130, vcc
	v_cmp_le_i32_e32 vcc, v15, v245
	v_subrev_u32_e32 v15, 24, v0
	s_nop 0
	v_cndmask_b32_e32 v115, v234, v115, vcc
	v_cmp_le_i32_e32 vcc, v15, v245
	v_subrev_u32_e32 v15, 51, v0
	s_nop 0
	v_cndmask_b32_e32 v131, v234, v131, vcc
	v_cmp_le_i32_e32 vcc, v15, v245
	v_subrev_u32_e32 v15, 19, v0
	s_nop 0
	v_cndmask_b32_e32 v116, v234, v116, vcc
	v_cmp_le_i32_e32 vcc, v15, v245
	v_subrev_u32_e32 v15, 50, v0
	s_nop 0
	v_cndmask_b32_e32 v132, v234, v132, vcc
	v_cmp_le_i32_e32 vcc, v15, v245
	v_subrev_u32_e32 v15, 18, v0
	s_nop 0
	v_cndmask_b32_e32 v117, v234, v117, vcc
	v_cmp_le_i32_e32 vcc, v15, v245
	v_subrev_u32_e32 v15, 49, v0
	s_nop 0
	v_cndmask_b32_e32 v133, v234, v133, vcc
	v_cmp_le_i32_e32 vcc, v15, v245
	v_subrev_u32_e32 v15, 17, v0
	s_nop 0
	v_cndmask_b32_e32 v118, v234, v118, vcc
	v_cmp_le_i32_e32 vcc, v15, v245
	v_subrev_u32_e32 v15, 48, v0
	s_nop 0
	v_cndmask_b32_e32 v134, v234, v134, vcc
	v_cmp_le_i32_e32 vcc, v15, v245
	v_add_u32_e32 v15, -16, v0
	s_nop 0
	v_cndmask_b32_e32 v119, v234, v119, vcc
	v_cmp_le_i32_e32 vcc, v15, v245
	v_subrev_u32_e32 v15, 43, v0
	s_nop 0
	v_cndmask_b32_e32 v135, v234, v135, vcc
	v_cmp_le_i32_e32 vcc, v15, v245
	v_add_u32_e32 v15, -11, v0
	s_nop 0
	v_cndmask_b32_e32 v120, v234, v120, vcc
	v_cmp_le_i32_e32 vcc, v15, v245
	v_subrev_u32_e32 v15, 42, v0
	s_nop 0
	v_cndmask_b32_e32 v136, v234, v136, vcc
	v_cmp_le_i32_e32 vcc, v15, v245
	v_add_u32_e32 v15, -10, v0
	s_nop 0
	v_cndmask_b32_e32 v121, v234, v121, vcc
	v_cmp_le_i32_e32 vcc, v15, v245
	v_subrev_u32_e32 v15, 41, v0
	s_nop 0
	v_cndmask_b32_e32 v137, v234, v137, vcc
	v_cmp_le_i32_e32 vcc, v15, v245
	v_add_u32_e32 v15, -9, v0
	s_nop 0
	v_cndmask_b32_e32 v122, v234, v122, vcc
	v_cmp_le_i32_e32 vcc, v15, v245
	v_subrev_u32_e32 v15, 40, v0
	s_nop 0
	v_cndmask_b32_e32 v138, v234, v138, vcc
	v_cmp_le_i32_e32 vcc, v15, v245
	v_add_u32_e32 v15, -8, v0
	s_nop 0
	v_cndmask_b32_e32 v123, v234, v123, vcc
	v_cmp_le_i32_e32 vcc, v15, v245
	v_subrev_u32_e32 v15, 35, v0
	s_nop 0
	v_cndmask_b32_e32 v139, v234, v139, vcc
	v_cmp_le_i32_e32 vcc, v15, v245
	v_add_u32_e32 v15, -3, v0
	s_nop 0
	v_cndmask_b32_e32 v124, v234, v124, vcc
	v_cmp_le_i32_e32 vcc, v15, v245
	v_subrev_u32_e32 v15, 34, v0
	s_nop 0
	v_cndmask_b32_e32 v140, v234, v140, vcc
	v_cmp_le_i32_e32 vcc, v15, v245
	v_add_u32_e32 v15, -2, v0
	s_nop 0
	v_cndmask_b32_e32 v125, v234, v125, vcc
	v_cmp_le_i32_e32 vcc, v15, v245
	v_subrev_u32_e32 v15, 33, v0
	s_nop 0
	v_cndmask_b32_e32 v141, v234, v141, vcc
	v_cmp_le_i32_e32 vcc, v15, v245
	v_add_u32_e32 v15, -1, v0
	s_nop 0
	v_cndmask_b32_e32 v126, v234, v126, vcc
	v_cmp_le_i32_e32 vcc, v15, v245
	v_subrev_u32_e32 v15, 32, v0
	s_nop 0
	v_cndmask_b32_e32 v142, v234, v142, vcc
	v_cmp_le_i32_e32 vcc, v15, v245
	s_nop 1
	v_cndmask_b32_e32 v127, v234, v127, vcc
	v_cmp_le_i32_e32 vcc, v0, v245
	s_nop 1
	v_cndmask_b32_e32 v143, v234, v143, vcc
